# fncontig: pipelined final RMSNorm with lane->element mapping that makes every store a contiguous 1 KiB (was 16-byte pieces on a 32-byte stride); on top of v83
# speedup vs baseline: 1.0137x; 1.0094x over previous
; #define GAS __attribute__((address_space(1)))
; __device__ __forceinline__ int lane_id_opaque() { int l; asm volatile("v_mbcnt_lo_u32_b32 %0, -1, 0\n\tv_mbcnt_hi_u32_b32 %0, -1, %0" : "=&v"(l)); return l; }
; __global__ void __launch_bounds__(NTHREADS, 2) __attribute__((amdgpu_waves_per_eu(2, 2))) hymba_fwd(Params p) {
;     ...
;         int tidf = wave_s * 64 + lane_id_opaque(); asm volatile("" : "+v"(tidf));
;         const int tid = tidf, lane = tid & 63, wave = tid >> 6;
;         const int gw = vcu * 8 + wave, NGW = G * 8;
;         f32x4 gf[4][2];
; #pragma unroll
;         for (int j = 0; j < 4; ++j) { gf[j][0] = ((const GAS f32x4*)p.final_norm)[2 * (lane + 64 * j)]; gf[j][1] = ((const GAS f32x4*)p.final_norm)[2 * (lane + 64 * j) + 1]; }
;         for (int row = gw; row < T_TOK; row += NGW) {
;             const GAS u32x4* yr = (const GAS u32x4*)((const GAS bf16_t*)(ws + WS_XN) + (size_t)row * 2048);
;             GAS f32x4* orow = (GAS f32x4*)((GAS float*)p.out + (size_t)row * 2048);
;             const float rs = rsqrtf(((const GAS float*)SSF)[row] * (1.0f / 2048.0f) + EPS);
; #pragma unroll
;             for (int j = 0; j < 4; ++j) {
;                 const u32x4 w = yr[lane + 64 * j];
.LBB0_772:
	v_mbcnt_lo_u32_b32 v0, -1, 0
	v_mbcnt_hi_u32_b32 v0, -1, v0
	v_readlane_b32 s0, v254, 0
	v_add_u32_e32 v0, s81, v0
	s_lshl_b32 s2, s0, 3
	v_ashrrev_i32_e32 v32, 6, v0
	v_add_u32_e32 v38, s2, v32
	s_mov_b32 s0, 0x8000
	v_cmp_gt_i32_e32 vcc, s0, v38
	s_and_saveexec_b64 s[0:1], vcc
	s_cbranch_execz .LBB0_775
	v_readlane_b32 s4, v254, 8
	v_and_b32_e32 v39, 63, v0
	v_readlane_b32 s12, v254, 16
	v_readlane_b32 s13, v254, 17
	v_readlane_b32 s14, v254, 18
	v_readlane_b32 s15, v254, 19
	v_readlane_b32 s16, v254, 20
	v_readlane_b32 s17, v254, 21
	v_lshlrev_b32_e32 v36, 5, v39
	v_mov_b32_e32 v37, 0
	v_readlane_b32 s18, v254, 22
	v_readlane_b32 s19, v254, 23
	s_mov_b64 s[12:13], s[16:17]
	v_lshl_add_u64 v[24:25], s[12:13], 0, v[36:37]
	s_mov_b64 s[0:1], 0x1000
	v_lshl_add_u64 v[26:27], v[24:25], 0, s[0:1]
	s_movk_i32 s0, 0x1000
	global_load_dwordx4 v[0:3], v36, s[12:13] offset:16
	global_load_dwordx4 v[4:7], v36, s[12:13]
	global_load_dwordx4 v[8:11], v36, s[12:13] offset:2064
	global_load_dwordx4 v[12:15], v36, s[12:13] offset:2048
	v_add_co_u32_e32 v34, vcc, s0, v24
	s_mov_b64 s[0:1], 0x1800
	s_nop 0
	v_addc_co_u32_e32 v35, vcc, 0, v25, vcc
	global_load_dwordx4 v[16:19], v[34:35], off
	global_load_dwordx4 v[20:23], v[26:27], off offset:16
	v_lshl_add_u64 v[40:41], v[24:25], 0, s[0:1]
	global_load_dwordx4 v[24:27], v[34:35], off offset:2048
	global_load_dwordx4 v[28:31], v[40:41], off offset:16
	v_ashrrev_i32_e32 v33, 31, v32
	s_ashr_i32 s3, s2, 31
	v_lshl_add_u64 v[40:41], v[32:33], 0, s[2:3]
	v_lshl_add_u64 v[32:33], v[40:41], 2, s[38:39]
	v_lshlrev_b64 v[34:35], 12, v[40:41]
	v_lshlrev_b64 v[40:41], 13, v[40:41]
	v_readlane_b32 s5, v254, 9
	v_readlane_b32 s6, v254, 10
	v_readlane_b32 s7, v254, 11
	s_mov_b64 s[14:15], s[18:19]
	s_lshl_b32 s0, s70, 3
	v_lshl_or_b32 v34, v39, 4, v34
	v_or_b32_e32 v40, v40, v36
	v_readlane_b32 s8, v254, 12
	v_readlane_b32 s9, v254, 13
	v_readlane_b32 s10, v254, 14
	v_readlane_b32 s11, v254, 15
	s_ashr_i32 s1, s0, 31
	v_lshl_add_u64 v[34:35], s[58:59], 0, v[34:35]
	s_mov_b64 s[4:5], 0xc00
	v_lshl_add_u64 v[36:37], s[14:15], 0, v[40:41]
	s_mov_b64 s[6:7], 0x1810
	s_lshl_b64 s[2:3], s[0:1], 2
	v_lshl_add_u64 v[34:35], v[34:35], 0, s[4:5]
	s_lshl_b64 s[4:5], s[0:1], 12
	v_lshl_add_u64 v[36:37], v[36:37], 0, s[6:7]
	s_lshl_b64 s[6:7], s[0:1], 13
	s_mov_b64 s[8:9], 0
	v_mov_b32_e32 v39, 0x358637bd
	s_mov_b32 s1, 0x800000
	s_movk_i32 s10, 0xf000
	s_movk_i32 s11, 0x7fff
	v_mbcnt_lo_u32_b32 v88, -1, 0
	v_mbcnt_hi_u32_b32 v88, -1, v88
	v_mov_b32_e32 v89, 0
	v_lshlrev_b32_e32 v90, 4, v88
	v_add_u32_e32 v91, 0x1000, v90
	global_load_dwordx4 v[0:3], v90, s[16:17]
	global_load_dwordx4 v[4:7], v90, s[16:17] offset:1024
	global_load_dwordx4 v[8:11], v90, s[16:17] offset:2048
	global_load_dwordx4 v[12:15], v90, s[16:17] offset:3072
	global_load_dwordx4 v[16:19], v91, s[16:17]
	global_load_dwordx4 v[20:23], v91, s[16:17] offset:1024
	global_load_dwordx4 v[24:27], v91, s[16:17] offset:2048
	global_load_dwordx4 v[28:31], v91, s[16:17] offset:3072
	v_lshlrev_b32_e32 v92, 3, v88
	v_add_u32_e32 v92, 0xc00, v92
	v_mov_b32_e32 v93, 0
	v_sub_co_u32_e32 v34, vcc, v34, v92
	s_nop 1
	v_subb_co_u32_e32 v35, vcc, v35, v93, vcc
	v_lshlrev_b32_e32 v92, 4, v88
	v_add_u32_e32 v92, 0x1810, v92
	v_sub_co_u32_e32 v36, vcc, v36, v92
	s_nop 1
	v_subb_co_u32_e32 v37, vcc, v37, v93, vcc
	v_add_co_u32_e32 v58, vcc, 0x1000, v36
	s_nop 1
	v_addc_co_u32_e32 v59, vcc, 0, v37, vcc
	s_mov_b32 s13, 8
	global_load_dword v56, v[32:33], off
	global_load_dwordx2 v[40:41], v[34:35], off
	global_load_dwordx2 v[42:43], v[34:35], off offset:512
	global_load_dwordx2 v[44:45], v[34:35], off offset:1024
	global_load_dwordx2 v[46:47], v[34:35], off offset:1536
	global_load_dwordx2 v[48:49], v[34:35], off offset:2048
	global_load_dwordx2 v[50:51], v[34:35], off offset:2560
	global_load_dwordx2 v[52:53], v[34:35], off offset:3072
	global_load_dwordx2 v[54:55], v[34:35], off offset:3584
	v_lshl_add_u64 v[32:33], v[32:33], 0, s[2:3]
	v_lshl_add_u64 v[34:35], v[34:35], 0, s[4:5]
.Lfn_loop:
	global_load_dword v76, v[32:33], off
	global_load_dwordx2 v[60:61], v[34:35], off
	global_load_dwordx2 v[62:63], v[34:35], off offset:512
	global_load_dwordx2 v[64:65], v[34:35], off offset:1024
	global_load_dwordx2 v[66:67], v[34:35], off offset:1536
	global_load_dwordx2 v[68:69], v[34:35], off offset:2048
	global_load_dwordx2 v[70:71], v[34:35], off offset:2560
	global_load_dwordx2 v[72:73], v[34:35], off offset:3072
	global_load_dwordx2 v[74:75], v[34:35], off offset:3584
	v_lshl_add_u64 v[32:33], v[32:33], 0, s[2:3]
	v_lshl_add_u64 v[34:35], v[34:35], 0, s[4:5]
	s_cmp_eq_u32 s13, 8
	s_cbranch_scc1 .Lfn_first
	s_waitcnt vmcnt(17)
	s_branch .Lfn_goA
.Lfn_first:
	s_waitcnt vmcnt(9)
; #define GAS __attribute__((address_space(1)))
; __device__ __forceinline__ float bf_lo(unsigned w) { return __uint_as_float(w << 16); }
; __device__ __forceinline__ float bf_hi(unsigned w) { return __uint_as_float(w & 0xffff0000u); }
; __global__ void __launch_bounds__(NTHREADS, 2) __attribute__((amdgpu_waves_per_eu(2, 2))) hymba_fwd(Params p) {
;     ...
;         for (int row = gw; row < T_TOK; row += NGW) {
;             const GAS u32x4* yr = (const GAS u32x4*)((const GAS bf16_t*)(ws + WS_XN) + (size_t)row * 2048);
;             GAS f32x4* orow = (GAS f32x4*)((GAS float*)p.out + (size_t)row * 2048);
;             const float rs = rsqrtf(((const GAS float*)SSF)[row] * (1.0f / 2048.0f) + EPS);
; #pragma unroll
;             for (int j = 0; j < 4; ++j) {
;                 const u32x4 w = yr[lane + 64 * j];
;                 orow[2 * (lane + 64 * j)] = (f32x4){bf_lo(w.x), bf_hi(w.x), bf_lo(w.y), bf_hi(w.y)} * rs * gf[j][0];
;                 orow[2 * (lane + 64 * j) + 1] = (f32x4){bf_lo(w.z), bf_hi(w.z), bf_lo(w.w), bf_hi(w.w)} * rs * gf[j][1];
;             }
.Lfn_goA:
	v_fmamk_f32 v78, v56, 0x3a000000, v39
	v_rsq_f32_e32 v78, v78
	v_lshlrev_b32_e32 v80, 16, v40
	v_and_b32_e32 v81, 0xffff0000, v40
	v_lshlrev_b32_e32 v82, 16, v41
	v_and_b32_e32 v83, 0xffff0000, v41
	v_pk_mul_f32 v[80:81], v[78:79], v[80:81] op_sel_hi:[0,1]
	v_pk_mul_f32 v[82:83], v[78:79], v[82:83] op_sel_hi:[0,1]
	v_pk_mul_f32 v[80:81], v[0:1], v[80:81]
	v_pk_mul_f32 v[82:83], v[2:3], v[82:83]
	global_store_dwordx4 v[36:37], v[80:83], off
	v_lshlrev_b32_e32 v84, 16, v42
	v_and_b32_e32 v85, 0xffff0000, v42
	v_lshlrev_b32_e32 v86, 16, v43
	v_and_b32_e32 v87, 0xffff0000, v43
	v_pk_mul_f32 v[84:85], v[78:79], v[84:85] op_sel_hi:[0,1]
	v_pk_mul_f32 v[86:87], v[78:79], v[86:87] op_sel_hi:[0,1]
	v_pk_mul_f32 v[84:85], v[4:5], v[84:85]
	v_pk_mul_f32 v[86:87], v[6:7], v[86:87]
	global_store_dwordx4 v[36:37], v[84:87], off offset:1024
	v_lshlrev_b32_e32 v80, 16, v44
	v_and_b32_e32 v81, 0xffff0000, v44
	v_lshlrev_b32_e32 v82, 16, v45
	v_and_b32_e32 v83, 0xffff0000, v45
	v_pk_mul_f32 v[80:81], v[78:79], v[80:81] op_sel_hi:[0,1]
	v_pk_mul_f32 v[82:83], v[78:79], v[82:83] op_sel_hi:[0,1]
	v_pk_mul_f32 v[80:81], v[8:9], v[80:81]
	v_pk_mul_f32 v[82:83], v[10:11], v[82:83]
	global_store_dwordx4 v[36:37], v[80:83], off offset:2048
	v_lshlrev_b32_e32 v84, 16, v46
	v_and_b32_e32 v85, 0xffff0000, v46
	v_lshlrev_b32_e32 v86, 16, v47
	v_and_b32_e32 v87, 0xffff0000, v47
	v_pk_mul_f32 v[84:85], v[78:79], v[84:85] op_sel_hi:[0,1]
	v_pk_mul_f32 v[86:87], v[78:79], v[86:87] op_sel_hi:[0,1]
	v_pk_mul_f32 v[84:85], v[12:13], v[84:85]
	v_pk_mul_f32 v[86:87], v[14:15], v[86:87]
	global_store_dwordx4 v[36:37], v[84:87], off offset:3072
	v_lshlrev_b32_e32 v80, 16, v48
	v_and_b32_e32 v81, 0xffff0000, v48
	v_lshlrev_b32_e32 v82, 16, v49
	v_and_b32_e32 v83, 0xffff0000, v49
	v_pk_mul_f32 v[80:81], v[78:79], v[80:81] op_sel_hi:[0,1]
	v_pk_mul_f32 v[82:83], v[78:79], v[82:83] op_sel_hi:[0,1]
	v_pk_mul_f32 v[80:81], v[16:17], v[80:81]
	v_pk_mul_f32 v[82:83], v[18:19], v[82:83]
	global_store_dwordx4 v[58:59], v[80:83], off
	v_lshlrev_b32_e32 v84, 16, v50
	v_and_b32_e32 v85, 0xffff0000, v50
	v_lshlrev_b32_e32 v86, 16, v51
	v_and_b32_e32 v87, 0xffff0000, v51
	v_pk_mul_f32 v[84:85], v[78:79], v[84:85] op_sel_hi:[0,1]
	v_pk_mul_f32 v[86:87], v[78:79], v[86:87] op_sel_hi:[0,1]
	v_pk_mul_f32 v[84:85], v[20:21], v[84:85]
	v_pk_mul_f32 v[86:87], v[22:23], v[86:87]
	global_store_dwordx4 v[58:59], v[84:87], off offset:1024
	v_lshlrev_b32_e32 v80, 16, v52
	v_and_b32_e32 v81, 0xffff0000, v52
	v_lshlrev_b32_e32 v82, 16, v53
	v_and_b32_e32 v83, 0xffff0000, v53
	v_pk_mul_f32 v[80:81], v[78:79], v[80:81] op_sel_hi:[0,1]
	v_pk_mul_f32 v[82:83], v[78:79], v[82:83] op_sel_hi:[0,1]
	v_pk_mul_f32 v[80:81], v[24:25], v[80:81]
	v_pk_mul_f32 v[82:83], v[26:27], v[82:83]
	global_store_dwordx4 v[58:59], v[80:83], off offset:2048
	v_lshlrev_b32_e32 v84, 16, v54
	v_and_b32_e32 v85, 0xffff0000, v54
	v_lshlrev_b32_e32 v86, 16, v55
	v_and_b32_e32 v87, 0xffff0000, v55
	v_pk_mul_f32 v[84:85], v[78:79], v[84:85] op_sel_hi:[0,1]
	v_pk_mul_f32 v[86:87], v[78:79], v[86:87] op_sel_hi:[0,1]
	v_pk_mul_f32 v[84:85], v[28:29], v[84:85]
	v_pk_mul_f32 v[86:87], v[30:31], v[86:87]
	global_store_dwordx4 v[58:59], v[84:87], off offset:3072
	v_lshl_add_u64 v[36:37], v[36:37], 0, s[6:7]
	v_lshl_add_u64 v[58:59], v[58:59], 0, s[6:7]
	s_cmp_eq_u32 s13, 1
	s_cbranch_scc1 .Lfn_last
	global_load_dword v56, v[32:33], off
	global_load_dwordx2 v[40:41], v[34:35], off
	global_load_dwordx2 v[42:43], v[34:35], off offset:512
	global_load_dwordx2 v[44:45], v[34:35], off offset:1024
	global_load_dwordx2 v[46:47], v[34:35], off offset:1536
	global_load_dwordx2 v[48:49], v[34:35], off offset:2048
	global_load_dwordx2 v[50:51], v[34:35], off offset:2560
	global_load_dwordx2 v[52:53], v[34:35], off offset:3072
	global_load_dwordx2 v[54:55], v[34:35], off offset:3584
	v_lshl_add_u64 v[32:33], v[32:33], 0, s[2:3]
	v_lshl_add_u64 v[34:35], v[34:35], 0, s[4:5]
	s_waitcnt vmcnt(17)
; #define GAS __attribute__((address_space(1)))
; __device__ __forceinline__ float bf_lo(unsigned w) { return __uint_as_float(w << 16); }
; __device__ __forceinline__ float bf_hi(unsigned w) { return __uint_as_float(w & 0xffff0000u); }
; __global__ void __launch_bounds__(NTHREADS, 2) __attribute__((amdgpu_waves_per_eu(2, 2))) hymba_fwd(Params p) {
;     ...
;         for (int row = gw; row < T_TOK; row += NGW) {
;             const GAS u32x4* yr = (const GAS u32x4*)((const GAS bf16_t*)(ws + WS_XN) + (size_t)row * 2048);
;             GAS f32x4* orow = (GAS f32x4*)((GAS float*)p.out + (size_t)row * 2048);
;             const float rs = rsqrtf(((const GAS float*)SSF)[row] * (1.0f / 2048.0f) + EPS);
; #pragma unroll
;             for (int j = 0; j < 4; ++j) {
;                 const u32x4 w = yr[lane + 64 * j];
;                 orow[2 * (lane + 64 * j)] = (f32x4){bf_lo(w.x), bf_hi(w.x), bf_lo(w.y), bf_hi(w.y)} * rs * gf[j][0];
;                 orow[2 * (lane + 64 * j) + 1] = (f32x4){bf_lo(w.z), bf_hi(w.z), bf_lo(w.w), bf_hi(w.w)} * rs * gf[j][1];
;             }
	v_fmamk_f32 v78, v76, 0x3a000000, v39
	v_rsq_f32_e32 v78, v78
	v_lshlrev_b32_e32 v80, 16, v60
	v_and_b32_e32 v81, 0xffff0000, v60
	v_lshlrev_b32_e32 v82, 16, v61
	v_and_b32_e32 v83, 0xffff0000, v61
	v_pk_mul_f32 v[80:81], v[78:79], v[80:81] op_sel_hi:[0,1]
	v_pk_mul_f32 v[82:83], v[78:79], v[82:83] op_sel_hi:[0,1]
	v_pk_mul_f32 v[80:81], v[0:1], v[80:81]
	v_pk_mul_f32 v[82:83], v[2:3], v[82:83]
	global_store_dwordx4 v[36:37], v[80:83], off
	v_lshlrev_b32_e32 v84, 16, v62
	v_and_b32_e32 v85, 0xffff0000, v62
	v_lshlrev_b32_e32 v86, 16, v63
	v_and_b32_e32 v87, 0xffff0000, v63
	v_pk_mul_f32 v[84:85], v[78:79], v[84:85] op_sel_hi:[0,1]
	v_pk_mul_f32 v[86:87], v[78:79], v[86:87] op_sel_hi:[0,1]
	v_pk_mul_f32 v[84:85], v[4:5], v[84:85]
	v_pk_mul_f32 v[86:87], v[6:7], v[86:87]
	global_store_dwordx4 v[36:37], v[84:87], off offset:1024
	v_lshlrev_b32_e32 v80, 16, v64
	v_and_b32_e32 v81, 0xffff0000, v64
	v_lshlrev_b32_e32 v82, 16, v65
	v_and_b32_e32 v83, 0xffff0000, v65
	v_pk_mul_f32 v[80:81], v[78:79], v[80:81] op_sel_hi:[0,1]
	v_pk_mul_f32 v[82:83], v[78:79], v[82:83] op_sel_hi:[0,1]
	v_pk_mul_f32 v[80:81], v[8:9], v[80:81]
	v_pk_mul_f32 v[82:83], v[10:11], v[82:83]
	global_store_dwordx4 v[36:37], v[80:83], off offset:2048
	v_lshlrev_b32_e32 v84, 16, v66
	v_and_b32_e32 v85, 0xffff0000, v66
	v_lshlrev_b32_e32 v86, 16, v67
	v_and_b32_e32 v87, 0xffff0000, v67
	v_pk_mul_f32 v[84:85], v[78:79], v[84:85] op_sel_hi:[0,1]
	v_pk_mul_f32 v[86:87], v[78:79], v[86:87] op_sel_hi:[0,1]
	v_pk_mul_f32 v[84:85], v[12:13], v[84:85]
	v_pk_mul_f32 v[86:87], v[14:15], v[86:87]
	global_store_dwordx4 v[36:37], v[84:87], off offset:3072
	v_lshlrev_b32_e32 v80, 16, v68
	v_and_b32_e32 v81, 0xffff0000, v68
	v_lshlrev_b32_e32 v82, 16, v69
	v_and_b32_e32 v83, 0xffff0000, v69
	v_pk_mul_f32 v[80:81], v[78:79], v[80:81] op_sel_hi:[0,1]
	v_pk_mul_f32 v[82:83], v[78:79], v[82:83] op_sel_hi:[0,1]
	v_pk_mul_f32 v[80:81], v[16:17], v[80:81]
	v_pk_mul_f32 v[82:83], v[18:19], v[82:83]
	global_store_dwordx4 v[58:59], v[80:83], off
	v_lshlrev_b32_e32 v84, 16, v70
	v_and_b32_e32 v85, 0xffff0000, v70
	v_lshlrev_b32_e32 v86, 16, v71
	v_and_b32_e32 v87, 0xffff0000, v71
	v_pk_mul_f32 v[84:85], v[78:79], v[84:85] op_sel_hi:[0,1]
	v_pk_mul_f32 v[86:87], v[78:79], v[86:87] op_sel_hi:[0,1]
	v_pk_mul_f32 v[84:85], v[20:21], v[84:85]
	v_pk_mul_f32 v[86:87], v[22:23], v[86:87]
	global_store_dwordx4 v[58:59], v[84:87], off offset:1024
	v_lshlrev_b32_e32 v80, 16, v72
	v_and_b32_e32 v81, 0xffff0000, v72
	v_lshlrev_b32_e32 v82, 16, v73
	v_and_b32_e32 v83, 0xffff0000, v73
	v_pk_mul_f32 v[80:81], v[78:79], v[80:81] op_sel_hi:[0,1]
	v_pk_mul_f32 v[82:83], v[78:79], v[82:83] op_sel_hi:[0,1]
	v_pk_mul_f32 v[80:81], v[24:25], v[80:81]
	v_pk_mul_f32 v[82:83], v[26:27], v[82:83]
	global_store_dwordx4 v[58:59], v[80:83], off offset:2048
	v_lshlrev_b32_e32 v84, 16, v74
	v_and_b32_e32 v85, 0xffff0000, v74
	v_lshlrev_b32_e32 v86, 16, v75
	v_and_b32_e32 v87, 0xffff0000, v75
	v_pk_mul_f32 v[84:85], v[78:79], v[84:85] op_sel_hi:[0,1]
	v_pk_mul_f32 v[86:87], v[78:79], v[86:87] op_sel_hi:[0,1]
	v_pk_mul_f32 v[84:85], v[28:29], v[84:85]
	v_pk_mul_f32 v[86:87], v[30:31], v[86:87]
	global_store_dwordx4 v[58:59], v[84:87], off offset:3072
	v_lshl_add_u64 v[36:37], v[36:37], 0, s[6:7]
	v_lshl_add_u64 v[58:59], v[58:59], 0, s[6:7]
	s_sub_u32 s13, s13, 1
	s_branch .Lfn_loop
.Lfn_last:
	s_waitcnt vmcnt(8)
	v_fmamk_f32 v78, v76, 0x3a000000, v39
	v_rsq_f32_e32 v78, v78
	v_lshlrev_b32_e32 v80, 16, v60
	v_and_b32_e32 v81, 0xffff0000, v60
	v_lshlrev_b32_e32 v82, 16, v61
	v_and_b32_e32 v83, 0xffff0000, v61
	v_pk_mul_f32 v[80:81], v[78:79], v[80:81] op_sel_hi:[0,1]
	v_pk_mul_f32 v[82:83], v[78:79], v[82:83] op_sel_hi:[0,1]
	v_pk_mul_f32 v[80:81], v[0:1], v[80:81]
	v_pk_mul_f32 v[82:83], v[2:3], v[82:83]
	global_store_dwordx4 v[36:37], v[80:83], off
	v_lshlrev_b32_e32 v84, 16, v62
	v_and_b32_e32 v85, 0xffff0000, v62
	v_lshlrev_b32_e32 v86, 16, v63
	v_and_b32_e32 v87, 0xffff0000, v63
	v_pk_mul_f32 v[84:85], v[78:79], v[84:85] op_sel_hi:[0,1]
	v_pk_mul_f32 v[86:87], v[78:79], v[86:87] op_sel_hi:[0,1]
	v_pk_mul_f32 v[84:85], v[4:5], v[84:85]
	v_pk_mul_f32 v[86:87], v[6:7], v[86:87]
	global_store_dwordx4 v[36:37], v[84:87], off offset:1024
	v_lshlrev_b32_e32 v80, 16, v64
	v_and_b32_e32 v81, 0xffff0000, v64
	v_lshlrev_b32_e32 v82, 16, v65
	v_and_b32_e32 v83, 0xffff0000, v65
	v_pk_mul_f32 v[80:81], v[78:79], v[80:81] op_sel_hi:[0,1]
	v_pk_mul_f32 v[82:83], v[78:79], v[82:83] op_sel_hi:[0,1]
	v_pk_mul_f32 v[80:81], v[8:9], v[80:81]
	v_pk_mul_f32 v[82:83], v[10:11], v[82:83]
	global_store_dwordx4 v[36:37], v[80:83], off offset:2048
	v_lshlrev_b32_e32 v84, 16, v66
	v_and_b32_e32 v85, 0xffff0000, v66
	v_lshlrev_b32_e32 v86, 16, v67
	v_and_b32_e32 v87, 0xffff0000, v67
	v_pk_mul_f32 v[84:85], v[78:79], v[84:85] op_sel_hi:[0,1]
	v_pk_mul_f32 v[86:87], v[78:79], v[86:87] op_sel_hi:[0,1]
	v_pk_mul_f32 v[84:85], v[12:13], v[84:85]
	v_pk_mul_f32 v[86:87], v[14:15], v[86:87]
	global_store_dwordx4 v[36:37], v[84:87], off offset:3072
	v_lshlrev_b32_e32 v80, 16, v68
	v_and_b32_e32 v81, 0xffff0000, v68
	v_lshlrev_b32_e32 v82, 16, v69
	v_and_b32_e32 v83, 0xffff0000, v69
	v_pk_mul_f32 v[80:81], v[78:79], v[80:81] op_sel_hi:[0,1]
	v_pk_mul_f32 v[82:83], v[78:79], v[82:83] op_sel_hi:[0,1]
	v_pk_mul_f32 v[80:81], v[16:17], v[80:81]
	v_pk_mul_f32 v[82:83], v[18:19], v[82:83]
	global_store_dwordx4 v[58:59], v[80:83], off
	v_lshlrev_b32_e32 v84, 16, v70
	v_and_b32_e32 v85, 0xffff0000, v70
	v_lshlrev_b32_e32 v86, 16, v71
	v_and_b32_e32 v87, 0xffff0000, v71
	v_pk_mul_f32 v[84:85], v[78:79], v[84:85] op_sel_hi:[0,1]
	v_pk_mul_f32 v[86:87], v[78:79], v[86:87] op_sel_hi:[0,1]
	v_pk_mul_f32 v[84:85], v[20:21], v[84:85]
	v_pk_mul_f32 v[86:87], v[22:23], v[86:87]
	global_store_dwordx4 v[58:59], v[84:87], off offset:1024
	v_lshlrev_b32_e32 v80, 16, v72
	v_and_b32_e32 v81, 0xffff0000, v72
	v_lshlrev_b32_e32 v82, 16, v73
	v_and_b32_e32 v83, 0xffff0000, v73
	v_pk_mul_f32 v[80:81], v[78:79], v[80:81] op_sel_hi:[0,1]
	v_pk_mul_f32 v[82:83], v[78:79], v[82:83] op_sel_hi:[0,1]
	v_pk_mul_f32 v[80:81], v[24:25], v[80:81]
	v_pk_mul_f32 v[82:83], v[26:27], v[82:83]
	global_store_dwordx4 v[58:59], v[80:83], off offset:2048
	v_lshlrev_b32_e32 v84, 16, v74
	v_and_b32_e32 v85, 0xffff0000, v74
	v_lshlrev_b32_e32 v86, 16, v75
	v_and_b32_e32 v87, 0xffff0000, v75
	v_pk_mul_f32 v[84:85], v[78:79], v[84:85] op_sel_hi:[0,1]
	v_pk_mul_f32 v[86:87], v[78:79], v[86:87] op_sel_hi:[0,1]
	v_pk_mul_f32 v[84:85], v[28:29], v[84:85]
	v_pk_mul_f32 v[86:87], v[30:31], v[86:87]
	global_store_dwordx4 v[58:59], v[84:87], off offset:3072
	v_lshl_add_u64 v[36:37], v[36:37], 0, s[6:7]
	v_lshl_add_u64 v[58:59], v[58:59], 0, s[6:7]
